# t1 + in-proj round-2 completion counted at the third tile's existing epilogue wait (no explicit store drain)
# speedup vs baseline: 1.0003x; 1.0003x over previous
.LBB0_241:
	v_ashrrev_i32_e32 v151, 31, v150
	v_lshl_add_u64 v[154:155], v[150:151], 2, s[66:67]
	global_load_dword v152, v[154:155], off
	global_load_dword v200, v[154:155], off offset:64
	global_load_dword v201, v[154:155], off offset:128
	global_load_dword v202, v[154:155], off offset:192
	global_load_dword v203, v[154:155], off offset:512
	global_load_dword v204, v[154:155], off offset:576
	global_load_dword v205, v[154:155], off offset:640
	global_load_dword v206, v[154:155], off offset:704
	v_cndmask_b32_e64 v153, 0, 1, s[60:61]
	v_cmp_ne_u32_e64 s[6:7], 1, v153
	s_andn2_b64 vcc, exec, s[60:61]
	s_waitcnt vmcnt(0)
	s_cmp_lg_u32 s83, 3
	s_cbranch_scc1 .Lp1_r1_skip
	s_mov_b64 exec, 1
	v_mov_b32_e32 v234, 0x3800
	v_mov_b32_e32 v235, 1
	global_atomic_add v234, v235, s[96:97]
	s_mov_b64 exec, -1
.Lp1_r1_skip:
	v_mul_f32_e32 v153, 0x3e0293ee, v152
	v_cndmask_b32_e64 v170, v152, v153, s[56:57]
	v_pk_mul_f32 v[162:163], v[126:127], v[170:171] op_sel_hi:[1,0]
	v_pk_mul_f32 v[164:165], v[124:125], v[170:171] op_sel_hi:[1,0]
	v_pk_mul_f32 v[156:157], v[122:123], v[170:171] op_sel_hi:[1,0]
	v_pk_mul_f32 v[158:159], v[120:121], v[170:171] op_sel_hi:[1,0]
	v_mov_b32_e32 v166, v164
	v_mov_b32_e32 v167, v165
	v_mov_b32_e32 v172, v162
	v_mov_b32_e32 v173, v163
	v_mov_b32_e32 v168, v158
	v_mov_b32_e32 v169, v159
	v_mov_b32_e32 v176, v156
	v_mov_b32_e32 v177, v157
	s_cbranch_vccnz .LBB0_243
	v_mul_f32_e32 v153, 0xbfb8aa3b, v158
	v_exp_f32_e32 v153, v153
	v_mul_f32_e32 v166, 0xbfb8aa3b, v165
	v_mul_f32_e32 v167, 0xbfb8aa3b, v159
	v_exp_f32_e32 v166, v166
	v_exp_f32_e32 v167, v167
	v_add_f32_e32 v153, 1.0, v153
	v_rcp_f32_e32 v168, v153
	v_add_f32_e32 v153, 1.0, v166
	v_add_f32_e32 v166, 1.0, v167
	v_mul_f32_e32 v167, 0xbfb8aa3b, v162
	v_exp_f32_e32 v167, v167
	v_mul_f32_e32 v169, 0xbfb8aa3b, v156
	v_exp_f32_e32 v171, v169
	v_rcp_f32_e32 v169, v166
	v_add_f32_e32 v166, 1.0, v167
	v_mul_f32_e32 v167, 0xbfb8aa3b, v163
	v_mul_f32_e32 v152, 0xbfb8aa3b, v164
	v_rcp_f32_e32 v172, v166
	v_add_f32_e32 v166, 1.0, v171
	v_exp_f32_e32 v167, v167
	v_mul_f32_e32 v171, 0xbfb8aa3b, v157
	v_exp_f32_e32 v152, v152
	v_exp_f32_e32 v171, v171
	v_rcp_f32_e32 v174, v166
	v_add_f32_e32 v166, 1.0, v167
	v_add_f32_e32 v152, 1.0, v152
	v_rcp_f32_e32 v173, v166
	v_add_f32_e32 v166, 1.0, v171
	v_rcp_f32_e32 v152, v152
	v_rcp_f32_e32 v153, v153
	v_rcp_f32_e32 v175, v166
	v_pk_mul_f32 v[168:169], v[158:159], v[168:169]
	v_pk_mul_f32 v[172:173], v[162:163], v[172:173]
	v_pk_mul_f32 v[166:167], v[164:165], v[152:153]
	v_pk_mul_f32 v[176:177], v[156:157], v[174:175]

.LBB0_310:
	v_ashrrev_i32_e32 v151, 31, v150
	s_waitcnt lgkmcnt(0)
	v_lshl_add_u64 v[152:153], v[150:151], 2, s[66:67]
	v_lshlrev_b64 v[154:155], 7, v[150:151]
	global_load_dword v158, v[152:153], off
	v_lshl_add_u64 v[162:163], v[136:137], 0, v[154:155]
	v_lshl_add_u64 v[170:171], v[138:139], 0, v[154:155]
	global_load_dwordx4 v[154:157], v[162:163], off offset:16
	s_nop 0
	global_load_dwordx4 v[162:165], v[162:163], off
	s_nop 0
	global_load_dwordx4 v[166:169], v[170:171], off offset:16
	s_nop 0
	global_load_dwordx4 v[170:173], v[170:171], off
	s_waitcnt vmcnt(0)
	v_pk_mul_f32 v[118:119], v[118:119], v[158:159] op_sel_hi:[1,0]
	v_pk_mul_f32 v[126:127], v[126:127], v[158:159] op_sel_hi:[1,0]
	v_pk_mul_f32 v[116:117], v[116:117], v[158:159] op_sel_hi:[1,0]
	v_pk_mul_f32 v[174:175], v[172:173], v[118:119]
	v_pk_mul_f32 v[118:119], v[164:165], v[118:119]
	v_pk_mul_f32 v[112:113], v[112:113], v[158:159] op_sel_hi:[1,0]
	v_pk_mul_f32 v[124:125], v[124:125], v[158:159] op_sel_hi:[1,0]
	v_pk_mul_f32 v[176:177], v[170:171], v[116:117]
	v_pk_fma_f32 v[174:175], v[164:165], v[126:127], v[174:175] neg_lo:[0,0,1] neg_hi:[0,0,1]
	v_pk_mul_f32 v[116:117], v[162:163], v[116:117]
	v_pk_fma_f32 v[118:119], v[172:173], v[126:127], v[118:119]
	v_pk_mul_f32 v[120:121], v[120:121], v[158:159] op_sel_hi:[1,0]
	v_pk_mul_f32 v[114:115], v[114:115], v[158:159] op_sel_hi:[1,0]
	v_pk_mul_f32 v[126:127], v[112:113], v[166:167]
	v_pk_fma_f32 v[176:177], v[162:163], v[124:125], v[176:177] neg_lo:[0,0,1] neg_hi:[0,0,1]
	v_pk_fma_f32 v[116:117], v[170:171], v[124:125], v[116:117]
	v_pk_mul_f32 v[122:123], v[122:123], v[158:159] op_sel_hi:[1,0]
	v_pk_mul_f32 v[124:125], v[114:115], v[168:169]
	v_pk_fma_f32 v[126:127], v[154:155], v[120:121], v[126:127] neg_lo:[0,0,1] neg_hi:[0,0,1]
	v_pk_mul_f32 v[120:121], v[120:121], v[166:167]
	v_pk_fma_f32 v[124:125], v[156:157], v[122:123], v[124:125] neg_lo:[0,0,1] neg_hi:[0,0,1]
	v_pk_mul_f32 v[122:123], v[122:123], v[168:169]
	v_pk_fma_f32 v[120:121], v[154:155], v[112:113], v[120:121]
	v_pk_fma_f32 v[122:123], v[156:157], v[114:115], v[122:123]
	v_cvt_pk_bf16_f32 v112, v176, v177
	v_cvt_pk_bf16_f32 v113, v174, v175
	v_cvt_pk_bf16_f32 v114, v126, v127
	v_cvt_pk_bf16_f32 v115, v124, v125
	v_cvt_pk_bf16_f32 v116, v116, v117
	v_cvt_pk_bf16_f32 v117, v118, v119
	v_cvt_pk_bf16_f32 v118, v120, v121
	v_mad_i64_i32 v[120:121], s[0:1], v150, s82, v[140:141]
	v_cvt_pk_bf16_f32 v119, v122, v123
	global_load_dword v222, v[152:153], off offset:64
	v_or_b32_e32 v208, 16, v150
	v_ashrrev_i32_e32 v209, 31, v208
	v_lshlrev_b64 v[210:211], 7, v[208:209]
	v_lshl_add_u64 v[214:215], v[136:137], 0, v[210:211]
	v_lshl_add_u64 v[224:225], v[138:139], 0, v[210:211]
	global_load_dwordx4 v[210:213], v[214:215], off offset:16
	global_load_dwordx4 v[214:217], v[214:215], off
	global_load_dwordx4 v[218:221], v[224:225], off offset:16
	global_load_dwordx4 v[224:227], v[224:225], off
	global_store_dwordx4 v[120:121], v[112:115], off offset:256
	global_store_dwordx4 v[120:121], v[116:119], off offset:320
	global_store_dwordx4 v[120:121], v[112:115], off offset:640
	global_store_dwordx4 v[120:121], v[116:119], off offset:704
	global_store_dwordx4 v[120:121], v[112:115], off offset:1024
	global_store_dwordx4 v[120:121], v[116:119], off offset:1088
	global_store_dwordx4 v[120:121], v[112:115], off offset:1408
	global_store_dwordx4 v[120:121], v[116:119], off offset:1472
	global_store_dwordx4 v[120:121], v[112:115], off offset:1792
	global_store_dwordx4 v[120:121], v[116:119], off offset:1856
	global_store_dwordx4 v[120:121], v[112:115], off offset:2176
	global_store_dwordx4 v[120:121], v[116:119], off offset:2240
	global_store_dwordx4 v[120:121], v[112:115], off offset:2560
	global_store_dwordx4 v[120:121], v[116:119], off offset:2624
	global_store_dwordx4 v[120:121], v[112:115], off offset:2944
	global_store_dwordx4 v[120:121], v[116:119], off offset:3008
	v_or_b32_e32 v112, 16, v150
	v_ashrrev_i32_e32 v113, 31, v112
	v_lshlrev_b64 v[114:115], 7, v[112:113]
	v_lshl_add_u64 v[118:119], v[136:137], 0, v[114:115]
	v_lshl_add_u64 v[154:155], v[138:139], 0, v[114:115]
	s_waitcnt vmcnt(16)
	v_mov_b32_e32 v126, v222
	v_mov_b32_e32 v114, v210
	v_mov_b32_e32 v115, v211
	v_mov_b32_e32 v116, v212
	v_mov_b32_e32 v117, v213
	v_mov_b32_e32 v118, v214
	v_mov_b32_e32 v119, v215
	v_mov_b32_e32 v120, v216
	v_mov_b32_e32 v121, v217
	v_mov_b32_e32 v122, v218
	v_mov_b32_e32 v123, v219
	v_mov_b32_e32 v124, v220
	v_mov_b32_e32 v125, v221
	v_mov_b32_e32 v154, v224
	v_mov_b32_e32 v155, v225
	v_mov_b32_e32 v156, v226
	v_mov_b32_e32 v157, v227
	v_pk_mul_f32 v[102:103], v[102:103], v[126:127] op_sel_hi:[1,0]
	v_pk_mul_f32 v[110:111], v[110:111], v[126:127] op_sel_hi:[1,0]
	v_pk_mul_f32 v[100:101], v[100:101], v[126:127] op_sel_hi:[1,0]
	v_pk_mul_f32 v[96:97], v[96:97], v[126:127] op_sel_hi:[1,0]
	v_pk_mul_f32 v[108:109], v[108:109], v[126:127] op_sel_hi:[1,0]
	v_pk_mul_f32 v[104:105], v[104:105], v[126:127] op_sel_hi:[1,0]
	s_nop 0
	v_pk_mul_f32 v[158:159], v[156:157], v[102:103]
	v_pk_mul_f32 v[102:103], v[120:121], v[102:103]
	v_pk_mul_f32 v[162:163], v[154:155], v[100:101]
	v_pk_fma_f32 v[158:159], v[120:121], v[110:111], v[158:159] neg_lo:[0,0,1] neg_hi:[0,0,1]
	v_pk_mul_f32 v[100:101], v[118:119], v[100:101]
	v_pk_fma_f32 v[102:103], v[156:157], v[110:111], v[102:103]
	v_pk_mul_f32 v[98:99], v[98:99], v[126:127] op_sel_hi:[1,0]
	v_pk_mul_f32 v[110:111], v[96:97], v[122:123]
	v_pk_fma_f32 v[162:163], v[118:119], v[108:109], v[162:163] neg_lo:[0,0,1] neg_hi:[0,0,1]
	v_pk_fma_f32 v[100:101], v[154:155], v[108:109], v[100:101]
	v_pk_mul_f32 v[106:107], v[106:107], v[126:127] op_sel_hi:[1,0]
	v_pk_mul_f32 v[108:109], v[98:99], v[124:125]
	v_pk_fma_f32 v[110:111], v[114:115], v[104:105], v[110:111] neg_lo:[0,0,1] neg_hi:[0,0,1]
	v_pk_mul_f32 v[104:105], v[104:105], v[122:123]
	v_pk_fma_f32 v[108:109], v[116:117], v[106:107], v[108:109] neg_lo:[0,0,1] neg_hi:[0,0,1]
	v_pk_mul_f32 v[106:107], v[106:107], v[124:125]
	v_pk_fma_f32 v[104:105], v[114:115], v[96:97], v[104:105]
	v_pk_fma_f32 v[106:107], v[116:117], v[98:99], v[106:107]
	v_cvt_pk_bf16_f32 v96, v162, v163
	v_cvt_pk_bf16_f32 v97, v158, v159
	v_cvt_pk_bf16_f32 v98, v110, v111
	v_cvt_pk_bf16_f32 v99, v108, v109
	v_cvt_pk_bf16_f32 v100, v100, v101
	v_cvt_pk_bf16_f32 v101, v102, v103
	v_cvt_pk_bf16_f32 v102, v104, v105
	v_mad_i64_i32 v[104:105], s[0:1], v112, s82, v[140:141]
	v_cvt_pk_bf16_f32 v103, v106, v107
	global_load_dword v226, v[152:153], off offset:128
	v_or_b32_e32 v208, 32, v150
	v_ashrrev_i32_e32 v209, 31, v208
	v_lshlrev_b64 v[210:211], 7, v[208:209]
	v_lshl_add_u64 v[214:215], v[136:137], 0, v[210:211]
	v_lshl_add_u64 v[222:223], v[138:139], 0, v[210:211]
	global_load_dwordx4 v[210:213], v[214:215], off offset:16
	global_load_dwordx4 v[214:217], v[214:215], off
	global_load_dwordx4 v[218:221], v[222:223], off offset:16
	global_load_dwordx4 v[222:225], v[222:223], off
	global_store_dwordx4 v[104:105], v[96:99], off offset:256
	global_store_dwordx4 v[104:105], v[100:103], off offset:320
	global_store_dwordx4 v[104:105], v[96:99], off offset:640
	global_store_dwordx4 v[104:105], v[100:103], off offset:704
	global_store_dwordx4 v[104:105], v[96:99], off offset:1024
	global_store_dwordx4 v[104:105], v[100:103], off offset:1088
	global_store_dwordx4 v[104:105], v[96:99], off offset:1408
	global_store_dwordx4 v[104:105], v[100:103], off offset:1472
	global_store_dwordx4 v[104:105], v[96:99], off offset:1792
	global_store_dwordx4 v[104:105], v[100:103], off offset:1856
	global_store_dwordx4 v[104:105], v[96:99], off offset:2176
	global_store_dwordx4 v[104:105], v[100:103], off offset:2240
	global_store_dwordx4 v[104:105], v[96:99], off offset:2560
	global_store_dwordx4 v[104:105], v[100:103], off offset:2624
	global_store_dwordx4 v[104:105], v[96:99], off offset:2944
	global_store_dwordx4 v[104:105], v[100:103], off offset:3008
	v_or_b32_e32 v96, 32, v150
	v_ashrrev_i32_e32 v97, 31, v96
	v_lshlrev_b64 v[98:99], 7, v[96:97]
	v_lshl_add_u64 v[102:103], v[136:137], 0, v[98:99]
	v_lshl_add_u64 v[110:111], v[138:139], 0, v[98:99]
	s_waitcnt vmcnt(16)
	v_mov_b32_e32 v114, v226
	v_mov_b32_e32 v98, v210
	v_mov_b32_e32 v99, v211
	v_mov_b32_e32 v100, v212
	v_mov_b32_e32 v101, v213
	v_mov_b32_e32 v102, v214
	v_mov_b32_e32 v103, v215
	v_mov_b32_e32 v104, v216
	v_mov_b32_e32 v105, v217
	v_mov_b32_e32 v106, v218
	v_mov_b32_e32 v107, v219
	v_mov_b32_e32 v108, v220
	v_mov_b32_e32 v109, v221
	v_mov_b32_e32 v110, v222
	v_mov_b32_e32 v111, v223
	v_mov_b32_e32 v112, v224
	v_mov_b32_e32 v113, v225
	v_pk_mul_f32 v[86:87], v[86:87], v[114:115] op_sel_hi:[1,0]
	v_pk_mul_f32 v[94:95], v[94:95], v[114:115] op_sel_hi:[1,0]
	v_pk_mul_f32 v[84:85], v[84:85], v[114:115] op_sel_hi:[1,0]
	v_pk_mul_f32 v[80:81], v[80:81], v[114:115] op_sel_hi:[1,0]
	v_pk_mul_f32 v[92:93], v[92:93], v[114:115] op_sel_hi:[1,0]
	v_pk_mul_f32 v[88:89], v[88:89], v[114:115] op_sel_hi:[1,0]
	s_nop 0
	v_pk_mul_f32 v[116:117], v[112:113], v[86:87]
	v_pk_mul_f32 v[86:87], v[104:105], v[86:87]
	v_pk_mul_f32 v[118:119], v[110:111], v[84:85]
	v_pk_fma_f32 v[116:117], v[104:105], v[94:95], v[116:117] neg_lo:[0,0,1] neg_hi:[0,0,1]
	v_pk_mul_f32 v[84:85], v[102:103], v[84:85]
	v_pk_fma_f32 v[86:87], v[112:113], v[94:95], v[86:87]
	v_pk_mul_f32 v[82:83], v[82:83], v[114:115] op_sel_hi:[1,0]
	v_pk_mul_f32 v[94:95], v[80:81], v[106:107]
	v_pk_fma_f32 v[118:119], v[102:103], v[92:93], v[118:119] neg_lo:[0,0,1] neg_hi:[0,0,1]
	v_pk_fma_f32 v[84:85], v[110:111], v[92:93], v[84:85]
	v_pk_mul_f32 v[90:91], v[90:91], v[114:115] op_sel_hi:[1,0]
	v_pk_mul_f32 v[92:93], v[82:83], v[108:109]
	v_pk_fma_f32 v[94:95], v[98:99], v[88:89], v[94:95] neg_lo:[0,0,1] neg_hi:[0,0,1]
	v_pk_mul_f32 v[88:89], v[88:89], v[106:107]
	v_pk_fma_f32 v[92:93], v[100:101], v[90:91], v[92:93] neg_lo:[0,0,1] neg_hi:[0,0,1]
	v_pk_mul_f32 v[90:91], v[90:91], v[108:109]
	v_pk_fma_f32 v[88:89], v[98:99], v[80:81], v[88:89]
	v_pk_fma_f32 v[90:91], v[100:101], v[82:83], v[90:91]
	v_cvt_pk_bf16_f32 v80, v118, v119
	v_cvt_pk_bf16_f32 v81, v116, v117
	v_cvt_pk_bf16_f32 v82, v94, v95
	v_cvt_pk_bf16_f32 v83, v92, v93
	v_cvt_pk_bf16_f32 v84, v84, v85
	v_cvt_pk_bf16_f32 v85, v86, v87
	v_cvt_pk_bf16_f32 v86, v88, v89
	v_mad_i64_i32 v[88:89], s[0:1], v96, s82, v[140:141]
	v_cvt_pk_bf16_f32 v87, v90, v91
	global_load_dword v226, v[152:153], off offset:192
	v_or_b32_e32 v208, 48, v150
	v_ashrrev_i32_e32 v209, 31, v208
	v_lshlrev_b64 v[210:211], 7, v[208:209]
	v_lshl_add_u64 v[214:215], v[136:137], 0, v[210:211]
	v_lshl_add_u64 v[222:223], v[138:139], 0, v[210:211]
	global_load_dwordx4 v[210:213], v[214:215], off offset:16
	global_load_dwordx4 v[214:217], v[214:215], off
	global_load_dwordx4 v[218:221], v[222:223], off offset:16
	global_load_dwordx4 v[222:225], v[222:223], off
	global_store_dwordx4 v[88:89], v[80:83], off offset:256
	global_store_dwordx4 v[88:89], v[84:87], off offset:320
	global_store_dwordx4 v[88:89], v[80:83], off offset:640
	global_store_dwordx4 v[88:89], v[84:87], off offset:704
	global_store_dwordx4 v[88:89], v[80:83], off offset:1024
	global_store_dwordx4 v[88:89], v[84:87], off offset:1088
	global_store_dwordx4 v[88:89], v[80:83], off offset:1408
	global_store_dwordx4 v[88:89], v[84:87], off offset:1472
	global_store_dwordx4 v[88:89], v[80:83], off offset:1792
	global_store_dwordx4 v[88:89], v[84:87], off offset:1856
	global_store_dwordx4 v[88:89], v[80:83], off offset:2176
	global_store_dwordx4 v[88:89], v[84:87], off offset:2240
	global_store_dwordx4 v[88:89], v[80:83], off offset:2560
	global_store_dwordx4 v[88:89], v[84:87], off offset:2624
	global_store_dwordx4 v[88:89], v[80:83], off offset:2944
	global_store_dwordx4 v[88:89], v[84:87], off offset:3008
	v_or_b32_e32 v80, 48, v150
	v_ashrrev_i32_e32 v81, 31, v80
	v_lshlrev_b64 v[82:83], 7, v[80:81]
	v_lshl_add_u64 v[86:87], v[136:137], 0, v[82:83]
	v_lshl_add_u64 v[94:95], v[138:139], 0, v[82:83]
	s_waitcnt vmcnt(16)
	v_mov_b32_e32 v98, v226
	v_mov_b32_e32 v82, v210
	v_mov_b32_e32 v83, v211
	v_mov_b32_e32 v84, v212
	v_mov_b32_e32 v85, v213
	v_mov_b32_e32 v86, v214
	v_mov_b32_e32 v87, v215
	v_mov_b32_e32 v88, v216
	v_mov_b32_e32 v89, v217
	v_mov_b32_e32 v90, v218
	v_mov_b32_e32 v91, v219
	v_mov_b32_e32 v92, v220
	v_mov_b32_e32 v93, v221
	v_mov_b32_e32 v94, v222
	v_mov_b32_e32 v95, v223
	v_mov_b32_e32 v96, v224
	v_mov_b32_e32 v97, v225
	v_pk_mul_f32 v[70:71], v[70:71], v[98:99] op_sel_hi:[1,0]
	v_pk_mul_f32 v[78:79], v[78:79], v[98:99] op_sel_hi:[1,0]
	v_pk_mul_f32 v[68:69], v[68:69], v[98:99] op_sel_hi:[1,0]
	v_pk_mul_f32 v[64:65], v[64:65], v[98:99] op_sel_hi:[1,0]
	v_pk_mul_f32 v[76:77], v[76:77], v[98:99] op_sel_hi:[1,0]
	v_pk_mul_f32 v[72:73], v[72:73], v[98:99] op_sel_hi:[1,0]
	s_nop 0
	v_pk_mul_f32 v[100:101], v[96:97], v[70:71]
	v_pk_mul_f32 v[70:71], v[88:89], v[70:71]
	v_pk_mul_f32 v[102:103], v[94:95], v[68:69]
	v_pk_fma_f32 v[100:101], v[88:89], v[78:79], v[100:101] neg_lo:[0,0,1] neg_hi:[0,0,1]
	v_pk_mul_f32 v[68:69], v[86:87], v[68:69]
	v_pk_fma_f32 v[70:71], v[96:97], v[78:79], v[70:71]
	v_pk_mul_f32 v[66:67], v[66:67], v[98:99] op_sel_hi:[1,0]
	v_pk_mul_f32 v[78:79], v[64:65], v[90:91]
	v_pk_fma_f32 v[102:103], v[86:87], v[76:77], v[102:103] neg_lo:[0,0,1] neg_hi:[0,0,1]
	v_pk_fma_f32 v[68:69], v[94:95], v[76:77], v[68:69]
	v_pk_mul_f32 v[74:75], v[74:75], v[98:99] op_sel_hi:[1,0]
	v_pk_mul_f32 v[76:77], v[66:67], v[92:93]
	v_pk_fma_f32 v[78:79], v[82:83], v[72:73], v[78:79] neg_lo:[0,0,1] neg_hi:[0,0,1]
	v_pk_mul_f32 v[72:73], v[72:73], v[90:91]
	v_pk_fma_f32 v[76:77], v[84:85], v[74:75], v[76:77] neg_lo:[0,0,1] neg_hi:[0,0,1]
	v_pk_mul_f32 v[74:75], v[74:75], v[92:93]
	v_pk_fma_f32 v[72:73], v[82:83], v[64:65], v[72:73]
	v_pk_fma_f32 v[74:75], v[84:85], v[66:67], v[74:75]
	v_cvt_pk_bf16_f32 v64, v102, v103
	v_cvt_pk_bf16_f32 v65, v100, v101
	v_cvt_pk_bf16_f32 v66, v78, v79
	v_cvt_pk_bf16_f32 v67, v76, v77
	v_cvt_pk_bf16_f32 v68, v68, v69
	v_cvt_pk_bf16_f32 v69, v70, v71
	v_cvt_pk_bf16_f32 v70, v72, v73
	v_mad_i64_i32 v[72:73], s[0:1], v80, s82, v[140:141]
	v_cvt_pk_bf16_f32 v71, v74, v75
	global_load_dword v226, v[152:153], off offset:512
	v_add_u32_e32 v208, 0x80, v150
	v_ashrrev_i32_e32 v209, 31, v208
	v_lshlrev_b64 v[210:211], 7, v[208:209]
	v_lshl_add_u64 v[214:215], v[136:137], 0, v[210:211]
	v_lshl_add_u64 v[222:223], v[138:139], 0, v[210:211]
	global_load_dwordx4 v[210:213], v[214:215], off offset:16
	global_load_dwordx4 v[214:217], v[214:215], off
	global_load_dwordx4 v[218:221], v[222:223], off offset:16
	global_load_dwordx4 v[222:225], v[222:223], off
	global_store_dwordx4 v[72:73], v[64:67], off offset:256
	global_store_dwordx4 v[72:73], v[68:71], off offset:320
	global_store_dwordx4 v[72:73], v[64:67], off offset:640
	global_store_dwordx4 v[72:73], v[68:71], off offset:704
	global_store_dwordx4 v[72:73], v[64:67], off offset:1024
	global_store_dwordx4 v[72:73], v[68:71], off offset:1088
	global_store_dwordx4 v[72:73], v[64:67], off offset:1408
	global_store_dwordx4 v[72:73], v[68:71], off offset:1472
	global_store_dwordx4 v[72:73], v[64:67], off offset:1792
	global_store_dwordx4 v[72:73], v[68:71], off offset:1856
	global_store_dwordx4 v[72:73], v[64:67], off offset:2176
	global_store_dwordx4 v[72:73], v[68:71], off offset:2240
	global_store_dwordx4 v[72:73], v[64:67], off offset:2560
	global_store_dwordx4 v[72:73], v[68:71], off offset:2624
	global_store_dwordx4 v[72:73], v[64:67], off offset:2944
	global_store_dwordx4 v[72:73], v[68:71], off offset:3008
	v_add_u32_e32 v64, 0x80, v150
	v_ashrrev_i32_e32 v65, 31, v64
	v_lshlrev_b64 v[66:67], 7, v[64:65]
	v_lshl_add_u64 v[70:71], v[136:137], 0, v[66:67]
	v_lshl_add_u64 v[78:79], v[138:139], 0, v[66:67]
	s_waitcnt vmcnt(16)
	v_mov_b32_e32 v82, v226
	v_mov_b32_e32 v66, v210
	v_mov_b32_e32 v67, v211
	v_mov_b32_e32 v68, v212
	v_mov_b32_e32 v69, v213
	v_mov_b32_e32 v70, v214
	v_mov_b32_e32 v71, v215
	v_mov_b32_e32 v72, v216
	v_mov_b32_e32 v73, v217
	v_mov_b32_e32 v74, v218
	v_mov_b32_e32 v75, v219
	v_mov_b32_e32 v76, v220
	v_mov_b32_e32 v77, v221
	v_mov_b32_e32 v78, v222
	v_mov_b32_e32 v79, v223
	v_mov_b32_e32 v80, v224
	v_mov_b32_e32 v81, v225
	v_pk_mul_f32 v[54:55], v[54:55], v[82:83] op_sel_hi:[1,0]
	v_pk_mul_f32 v[62:63], v[62:63], v[82:83] op_sel_hi:[1,0]
	v_pk_mul_f32 v[52:53], v[52:53], v[82:83] op_sel_hi:[1,0]
	v_pk_mul_f32 v[48:49], v[48:49], v[82:83] op_sel_hi:[1,0]
	v_pk_mul_f32 v[60:61], v[60:61], v[82:83] op_sel_hi:[1,0]
	v_pk_mul_f32 v[56:57], v[56:57], v[82:83] op_sel_hi:[1,0]
	s_nop 0
	v_pk_mul_f32 v[84:85], v[80:81], v[54:55]
	v_pk_mul_f32 v[54:55], v[72:73], v[54:55]
	v_pk_mul_f32 v[86:87], v[78:79], v[52:53]
	v_pk_fma_f32 v[84:85], v[72:73], v[62:63], v[84:85] neg_lo:[0,0,1] neg_hi:[0,0,1]
	v_pk_mul_f32 v[52:53], v[70:71], v[52:53]
	v_pk_fma_f32 v[54:55], v[80:81], v[62:63], v[54:55]
	v_pk_mul_f32 v[50:51], v[50:51], v[82:83] op_sel_hi:[1,0]
	v_pk_mul_f32 v[62:63], v[48:49], v[74:75]
	v_pk_fma_f32 v[86:87], v[70:71], v[60:61], v[86:87] neg_lo:[0,0,1] neg_hi:[0,0,1]
	v_pk_fma_f32 v[52:53], v[78:79], v[60:61], v[52:53]
	v_pk_mul_f32 v[58:59], v[58:59], v[82:83] op_sel_hi:[1,0]
	v_pk_mul_f32 v[60:61], v[50:51], v[76:77]
	v_pk_fma_f32 v[62:63], v[66:67], v[56:57], v[62:63] neg_lo:[0,0,1] neg_hi:[0,0,1]
	v_pk_mul_f32 v[56:57], v[56:57], v[74:75]
	v_pk_fma_f32 v[60:61], v[68:69], v[58:59], v[60:61] neg_lo:[0,0,1] neg_hi:[0,0,1]
	v_pk_mul_f32 v[58:59], v[58:59], v[76:77]
	v_pk_fma_f32 v[56:57], v[66:67], v[48:49], v[56:57]
	v_pk_fma_f32 v[58:59], v[68:69], v[50:51], v[58:59]
	v_cvt_pk_bf16_f32 v48, v86, v87
	v_cvt_pk_bf16_f32 v49, v84, v85
	v_cvt_pk_bf16_f32 v50, v62, v63
	v_cvt_pk_bf16_f32 v51, v60, v61
	v_cvt_pk_bf16_f32 v52, v52, v53
	v_cvt_pk_bf16_f32 v53, v54, v55
	v_cvt_pk_bf16_f32 v54, v56, v57
	v_mad_i64_i32 v[56:57], s[0:1], v64, s82, v[140:141]
	v_cvt_pk_bf16_f32 v55, v58, v59
	global_load_dword v226, v[152:153], off offset:576
	v_add_u32_e32 v208, 0x90, v150
	v_ashrrev_i32_e32 v209, 31, v208
	v_lshlrev_b64 v[210:211], 7, v[208:209]
	v_lshl_add_u64 v[214:215], v[136:137], 0, v[210:211]
	v_lshl_add_u64 v[222:223], v[138:139], 0, v[210:211]
	global_load_dwordx4 v[210:213], v[214:215], off offset:16
	global_load_dwordx4 v[214:217], v[214:215], off
	global_load_dwordx4 v[218:221], v[222:223], off offset:16
	global_load_dwordx4 v[222:225], v[222:223], off
	global_store_dwordx4 v[56:57], v[48:51], off offset:256
	global_store_dwordx4 v[56:57], v[52:55], off offset:320
	global_store_dwordx4 v[56:57], v[48:51], off offset:640
	global_store_dwordx4 v[56:57], v[52:55], off offset:704
	global_store_dwordx4 v[56:57], v[48:51], off offset:1024
	global_store_dwordx4 v[56:57], v[52:55], off offset:1088
	global_store_dwordx4 v[56:57], v[48:51], off offset:1408
	global_store_dwordx4 v[56:57], v[52:55], off offset:1472
	global_store_dwordx4 v[56:57], v[48:51], off offset:1792
	global_store_dwordx4 v[56:57], v[52:55], off offset:1856
	global_store_dwordx4 v[56:57], v[48:51], off offset:2176
	global_store_dwordx4 v[56:57], v[52:55], off offset:2240
	global_store_dwordx4 v[56:57], v[48:51], off offset:2560
	global_store_dwordx4 v[56:57], v[52:55], off offset:2624
	global_store_dwordx4 v[56:57], v[48:51], off offset:2944
	global_store_dwordx4 v[56:57], v[52:55], off offset:3008
	v_add_u32_e32 v48, 0x90, v150
	v_ashrrev_i32_e32 v49, 31, v48
	v_lshlrev_b64 v[50:51], 7, v[48:49]
	v_lshl_add_u64 v[54:55], v[136:137], 0, v[50:51]
	v_lshl_add_u64 v[62:63], v[138:139], 0, v[50:51]
	s_waitcnt vmcnt(16)
	v_mov_b32_e32 v66, v226
	v_mov_b32_e32 v50, v210
	v_mov_b32_e32 v51, v211
	v_mov_b32_e32 v52, v212
	v_mov_b32_e32 v53, v213
	v_mov_b32_e32 v54, v214
	v_mov_b32_e32 v55, v215
	v_mov_b32_e32 v56, v216
	v_mov_b32_e32 v57, v217
	v_mov_b32_e32 v58, v218
	v_mov_b32_e32 v59, v219
	v_mov_b32_e32 v60, v220
	v_mov_b32_e32 v61, v221
	v_mov_b32_e32 v62, v222
	v_mov_b32_e32 v63, v223
	v_mov_b32_e32 v64, v224
	v_mov_b32_e32 v65, v225
	v_pk_mul_f32 v[38:39], v[38:39], v[66:67] op_sel_hi:[1,0]
	v_pk_mul_f32 v[46:47], v[46:47], v[66:67] op_sel_hi:[1,0]
	v_pk_mul_f32 v[36:37], v[36:37], v[66:67] op_sel_hi:[1,0]
	v_pk_mul_f32 v[32:33], v[32:33], v[66:67] op_sel_hi:[1,0]
	v_pk_mul_f32 v[44:45], v[44:45], v[66:67] op_sel_hi:[1,0]
	v_pk_mul_f32 v[40:41], v[40:41], v[66:67] op_sel_hi:[1,0]
	s_nop 0
	v_pk_mul_f32 v[68:69], v[64:65], v[38:39]
	v_pk_mul_f32 v[38:39], v[56:57], v[38:39]
	v_pk_mul_f32 v[70:71], v[62:63], v[36:37]
	v_pk_fma_f32 v[68:69], v[56:57], v[46:47], v[68:69] neg_lo:[0,0,1] neg_hi:[0,0,1]
	v_pk_mul_f32 v[36:37], v[54:55], v[36:37]
	v_pk_fma_f32 v[38:39], v[64:65], v[46:47], v[38:39]
	v_pk_mul_f32 v[34:35], v[34:35], v[66:67] op_sel_hi:[1,0]
	v_pk_mul_f32 v[46:47], v[32:33], v[58:59]
	v_pk_fma_f32 v[70:71], v[54:55], v[44:45], v[70:71] neg_lo:[0,0,1] neg_hi:[0,0,1]
	v_pk_fma_f32 v[36:37], v[62:63], v[44:45], v[36:37]
	v_pk_mul_f32 v[42:43], v[42:43], v[66:67] op_sel_hi:[1,0]
	v_pk_mul_f32 v[44:45], v[34:35], v[60:61]
	v_pk_fma_f32 v[46:47], v[50:51], v[40:41], v[46:47] neg_lo:[0,0,1] neg_hi:[0,0,1]
	v_pk_mul_f32 v[40:41], v[40:41], v[58:59]
	v_pk_fma_f32 v[44:45], v[52:53], v[42:43], v[44:45] neg_lo:[0,0,1] neg_hi:[0,0,1]
	v_pk_mul_f32 v[42:43], v[42:43], v[60:61]
	v_pk_fma_f32 v[40:41], v[50:51], v[32:33], v[40:41]
	v_pk_fma_f32 v[42:43], v[52:53], v[34:35], v[42:43]
	v_cvt_pk_bf16_f32 v32, v70, v71
	v_cvt_pk_bf16_f32 v33, v68, v69
	v_cvt_pk_bf16_f32 v34, v46, v47
	v_cvt_pk_bf16_f32 v35, v44, v45
	v_cvt_pk_bf16_f32 v36, v36, v37
	v_cvt_pk_bf16_f32 v37, v38, v39
	v_cvt_pk_bf16_f32 v38, v40, v41
	v_mad_i64_i32 v[40:41], s[0:1], v48, s82, v[140:141]
	v_cvt_pk_bf16_f32 v39, v42, v43
	global_load_dword v226, v[152:153], off offset:640
	v_add_u32_e32 v208, 0xa0, v150
	v_ashrrev_i32_e32 v209, 31, v208
	v_lshlrev_b64 v[210:211], 7, v[208:209]
	v_lshl_add_u64 v[214:215], v[136:137], 0, v[210:211]
	v_lshl_add_u64 v[222:223], v[138:139], 0, v[210:211]
	global_load_dwordx4 v[210:213], v[214:215], off offset:16
	global_load_dwordx4 v[214:217], v[214:215], off
	global_load_dwordx4 v[218:221], v[222:223], off offset:16
	global_load_dwordx4 v[222:225], v[222:223], off
	global_store_dwordx4 v[40:41], v[32:35], off offset:256
	global_store_dwordx4 v[40:41], v[36:39], off offset:320
	global_store_dwordx4 v[40:41], v[32:35], off offset:640
	global_store_dwordx4 v[40:41], v[36:39], off offset:704
	global_store_dwordx4 v[40:41], v[32:35], off offset:1024
	global_store_dwordx4 v[40:41], v[36:39], off offset:1088
	global_store_dwordx4 v[40:41], v[32:35], off offset:1408
	global_store_dwordx4 v[40:41], v[36:39], off offset:1472
	global_store_dwordx4 v[40:41], v[32:35], off offset:1792
	global_store_dwordx4 v[40:41], v[36:39], off offset:1856
	global_store_dwordx4 v[40:41], v[32:35], off offset:2176
	global_store_dwordx4 v[40:41], v[36:39], off offset:2240
	global_store_dwordx4 v[40:41], v[32:35], off offset:2560
	global_store_dwordx4 v[40:41], v[36:39], off offset:2624
	global_store_dwordx4 v[40:41], v[32:35], off offset:2944
	global_store_dwordx4 v[40:41], v[36:39], off offset:3008
	v_add_u32_e32 v32, 0xa0, v150
	v_ashrrev_i32_e32 v33, 31, v32
	v_lshlrev_b64 v[34:35], 7, v[32:33]
	v_lshl_add_u64 v[38:39], v[136:137], 0, v[34:35]
	v_lshl_add_u64 v[46:47], v[138:139], 0, v[34:35]
	s_waitcnt vmcnt(16)
	v_mov_b32_e32 v50, v226
	v_mov_b32_e32 v34, v210
	v_mov_b32_e32 v35, v211
	v_mov_b32_e32 v36, v212
	v_mov_b32_e32 v37, v213
	v_mov_b32_e32 v38, v214
	v_mov_b32_e32 v39, v215
	v_mov_b32_e32 v40, v216
	v_mov_b32_e32 v41, v217
	v_mov_b32_e32 v42, v218
	v_mov_b32_e32 v43, v219
	v_mov_b32_e32 v44, v220
	v_mov_b32_e32 v45, v221
	v_mov_b32_e32 v46, v222
	v_mov_b32_e32 v47, v223
	v_mov_b32_e32 v48, v224
	v_mov_b32_e32 v49, v225
	v_pk_mul_f32 v[22:23], v[22:23], v[50:51] op_sel_hi:[1,0]
	v_pk_mul_f32 v[30:31], v[30:31], v[50:51] op_sel_hi:[1,0]
	v_pk_mul_f32 v[20:21], v[20:21], v[50:51] op_sel_hi:[1,0]
	v_pk_mul_f32 v[16:17], v[16:17], v[50:51] op_sel_hi:[1,0]
	v_pk_mul_f32 v[28:29], v[28:29], v[50:51] op_sel_hi:[1,0]
	v_pk_mul_f32 v[24:25], v[24:25], v[50:51] op_sel_hi:[1,0]
	s_nop 0
	v_pk_mul_f32 v[52:53], v[48:49], v[22:23]
	v_pk_mul_f32 v[22:23], v[40:41], v[22:23]
	v_pk_mul_f32 v[54:55], v[46:47], v[20:21]
	v_pk_fma_f32 v[52:53], v[40:41], v[30:31], v[52:53] neg_lo:[0,0,1] neg_hi:[0,0,1]
	v_pk_mul_f32 v[20:21], v[38:39], v[20:21]
	v_pk_fma_f32 v[22:23], v[48:49], v[30:31], v[22:23]
	v_pk_mul_f32 v[18:19], v[18:19], v[50:51] op_sel_hi:[1,0]
	v_pk_mul_f32 v[30:31], v[16:17], v[42:43]
	v_pk_fma_f32 v[54:55], v[38:39], v[28:29], v[54:55] neg_lo:[0,0,1] neg_hi:[0,0,1]
	v_pk_fma_f32 v[20:21], v[46:47], v[28:29], v[20:21]
	v_pk_mul_f32 v[26:27], v[26:27], v[50:51] op_sel_hi:[1,0]
	v_pk_mul_f32 v[28:29], v[18:19], v[44:45]
	v_pk_fma_f32 v[30:31], v[34:35], v[24:25], v[30:31] neg_lo:[0,0,1] neg_hi:[0,0,1]
	v_pk_mul_f32 v[24:25], v[24:25], v[42:43]
	v_pk_fma_f32 v[28:29], v[36:37], v[26:27], v[28:29] neg_lo:[0,0,1] neg_hi:[0,0,1]
	v_pk_mul_f32 v[26:27], v[26:27], v[44:45]
	v_pk_fma_f32 v[24:25], v[34:35], v[16:17], v[24:25]
	v_pk_fma_f32 v[26:27], v[36:37], v[18:19], v[26:27]
	v_cvt_pk_bf16_f32 v16, v54, v55
	v_cvt_pk_bf16_f32 v17, v52, v53
	v_cvt_pk_bf16_f32 v18, v30, v31
	v_cvt_pk_bf16_f32 v19, v28, v29
	v_cvt_pk_bf16_f32 v20, v20, v21
	v_cvt_pk_bf16_f32 v21, v22, v23
	v_cvt_pk_bf16_f32 v22, v24, v25
	v_mad_i64_i32 v[24:25], s[0:1], v32, s82, v[140:141]
	v_cvt_pk_bf16_f32 v23, v26, v27
	global_load_dword v226, v[152:153], off offset:704
	v_add_u32_e32 v208, 0xb0, v150
	v_ashrrev_i32_e32 v209, 31, v208
	v_lshlrev_b64 v[210:211], 7, v[208:209]
	v_lshl_add_u64 v[214:215], v[136:137], 0, v[210:211]
	v_lshl_add_u64 v[222:223], v[138:139], 0, v[210:211]
	global_load_dwordx4 v[210:213], v[214:215], off offset:16
	global_load_dwordx4 v[214:217], v[214:215], off
	global_load_dwordx4 v[218:221], v[222:223], off offset:16
	global_load_dwordx4 v[222:225], v[222:223], off
	global_store_dwordx4 v[24:25], v[16:19], off offset:256
	global_store_dwordx4 v[24:25], v[20:23], off offset:320
	global_store_dwordx4 v[24:25], v[16:19], off offset:640
	global_store_dwordx4 v[24:25], v[20:23], off offset:704
	global_store_dwordx4 v[24:25], v[16:19], off offset:1024
	global_store_dwordx4 v[24:25], v[20:23], off offset:1088
	global_store_dwordx4 v[24:25], v[16:19], off offset:1408
	global_store_dwordx4 v[24:25], v[20:23], off offset:1472
	global_store_dwordx4 v[24:25], v[16:19], off offset:1792
	global_store_dwordx4 v[24:25], v[20:23], off offset:1856
	global_store_dwordx4 v[24:25], v[16:19], off offset:2176
	global_store_dwordx4 v[24:25], v[20:23], off offset:2240
	global_store_dwordx4 v[24:25], v[16:19], off offset:2560
	global_store_dwordx4 v[24:25], v[20:23], off offset:2624
	global_store_dwordx4 v[24:25], v[16:19], off offset:2944
	global_store_dwordx4 v[24:25], v[20:23], off offset:3008
	v_add_u32_e32 v16, 0xb0, v150
	v_ashrrev_i32_e32 v17, 31, v16
	v_lshlrev_b64 v[18:19], 7, v[16:17]
	v_lshl_add_u64 v[22:23], v[136:137], 0, v[18:19]
	v_lshl_add_u64 v[30:31], v[138:139], 0, v[18:19]
	s_waitcnt vmcnt(16)
	v_mov_b32_e32 v34, v226
	v_mov_b32_e32 v18, v210
	v_mov_b32_e32 v19, v211
	v_mov_b32_e32 v20, v212
	v_mov_b32_e32 v21, v213
	v_mov_b32_e32 v22, v214
	v_mov_b32_e32 v23, v215
	v_mov_b32_e32 v24, v216
	v_mov_b32_e32 v25, v217
	v_mov_b32_e32 v26, v218
	v_mov_b32_e32 v27, v219
	v_mov_b32_e32 v28, v220
	v_mov_b32_e32 v29, v221
	v_mov_b32_e32 v30, v222
	v_mov_b32_e32 v31, v223
	v_mov_b32_e32 v32, v224
	v_mov_b32_e32 v33, v225
	v_pk_mul_f32 v[6:7], v[6:7], v[34:35] op_sel_hi:[1,0]
	v_pk_mul_f32 v[14:15], v[14:15], v[34:35] op_sel_hi:[1,0]
	v_pk_mul_f32 v[4:5], v[4:5], v[34:35] op_sel_hi:[1,0]
	v_pk_mul_f32 v[0:1], v[0:1], v[34:35] op_sel_hi:[1,0]
	v_pk_mul_f32 v[12:13], v[12:13], v[34:35] op_sel_hi:[1,0]
	v_pk_mul_f32 v[8:9], v[8:9], v[34:35] op_sel_hi:[1,0]
	s_nop 0
	v_pk_mul_f32 v[36:37], v[32:33], v[6:7]
	v_pk_mul_f32 v[6:7], v[24:25], v[6:7]
	v_pk_mul_f32 v[38:39], v[30:31], v[4:5]
	v_pk_fma_f32 v[36:37], v[24:25], v[14:15], v[36:37] neg_lo:[0,0,1] neg_hi:[0,0,1]
	v_pk_mul_f32 v[4:5], v[22:23], v[4:5]
	v_pk_fma_f32 v[6:7], v[32:33], v[14:15], v[6:7]
	v_pk_mul_f32 v[2:3], v[2:3], v[34:35] op_sel_hi:[1,0]
	v_pk_mul_f32 v[14:15], v[0:1], v[26:27]
	v_pk_fma_f32 v[38:39], v[22:23], v[12:13], v[38:39] neg_lo:[0,0,1] neg_hi:[0,0,1]
	v_pk_fma_f32 v[4:5], v[30:31], v[12:13], v[4:5]
	v_pk_mul_f32 v[10:11], v[10:11], v[34:35] op_sel_hi:[1,0]
	v_pk_mul_f32 v[12:13], v[2:3], v[28:29]
	v_pk_fma_f32 v[14:15], v[18:19], v[8:9], v[14:15] neg_lo:[0,0,1] neg_hi:[0,0,1]
	v_pk_mul_f32 v[8:9], v[8:9], v[26:27]
	v_pk_fma_f32 v[12:13], v[20:21], v[10:11], v[12:13] neg_lo:[0,0,1] neg_hi:[0,0,1]
	v_pk_mul_f32 v[10:11], v[10:11], v[28:29]
	v_pk_fma_f32 v[8:9], v[18:19], v[0:1], v[8:9]
	v_pk_fma_f32 v[10:11], v[20:21], v[2:3], v[10:11]
	v_cvt_pk_bf16_f32 v0, v38, v39
	v_cvt_pk_bf16_f32 v1, v36, v37
	v_cvt_pk_bf16_f32 v2, v14, v15
	v_cvt_pk_bf16_f32 v3, v12, v13
	v_cvt_pk_bf16_f32 v4, v4, v5
	v_cvt_pk_bf16_f32 v5, v6, v7
	v_cvt_pk_bf16_f32 v6, v8, v9
	v_mad_i64_i32 v[8:9], s[0:1], v16, s82, v[140:141]
	v_cvt_pk_bf16_f32 v7, v10, v11
	global_store_dwordx4 v[8:9], v[0:3], off offset:256
	global_store_dwordx4 v[8:9], v[4:7], off offset:320
	global_store_dwordx4 v[8:9], v[0:3], off offset:640
	global_store_dwordx4 v[8:9], v[4:7], off offset:704
	global_store_dwordx4 v[8:9], v[0:3], off offset:1024
	global_store_dwordx4 v[8:9], v[4:7], off offset:1088
	global_store_dwordx4 v[8:9], v[0:3], off offset:1408
	global_store_dwordx4 v[8:9], v[4:7], off offset:1472
	global_store_dwordx4 v[8:9], v[0:3], off offset:1792
	global_store_dwordx4 v[8:9], v[4:7], off offset:1856
	global_store_dwordx4 v[8:9], v[0:3], off offset:2176
	global_store_dwordx4 v[8:9], v[4:7], off offset:2240
	global_store_dwordx4 v[8:9], v[0:3], off offset:2560
	global_store_dwordx4 v[8:9], v[4:7], off offset:2624
	global_store_dwordx4 v[8:9], v[0:3], off offset:2944
	global_store_dwordx4 v[8:9], v[4:7], off offset:3008
.LBB0_311:
	s_andn2_b64 vcc, exec, s[4:5]
	s_mov_b64 s[0:1], -1
	s_cbranch_vccnz .LBB0_214
	s_andn2_b64 vcc, exec, s[38:39]
	s_cbranch_vccnz .LBB0_213
	s_barrier
	s_branch .LBB0_213
